# j0 abs-max butterfly via DPP/permlane swaps (bit-identical max), on sc3
# speedup vs baseline: 1.0002x; 1.0002x over previous
; __device__ __forceinline__ void bias_scan(char*shm,const float*__restrict__ lf,float*gdst=nullptr){
;   const int tid=threadIdx.x,lane=tid&63,wid=tid>>6;
;   float*bias=(float*)(shm+LDS_BIAS); float*wtot=(float*)(shm+LDS_WS);
;   const f32x4v a=*(const f32x4v*)(lf+tid*8),b=*(const f32x4v*)(lf+tid*8+4);
;   const float s0=a[0],s1=s0+a[1],s2=s1+a[2],s3=s2+a[3],s4=s3+b[0],s5=s4+b[1],s6=s5+b[2],s7=s6+b[3];
;   float inc=s7;
;   #pragma unroll
;   for(int o=1;o<64;o<<=1){const float t=__shfl_up(inc,o); if(lane>=o)inc+=t;}
;   if(lane==63)wtot[wid]=inc;
;   asm volatile("s_waitcnt lgkmcnt(0)\n\ts_barrier":::"memory");
;   float base=0.f;
;   #pragma unroll
;   for(int w=0;w<NW;++w){const float x=wtot[w]; if(w<wid)base+=x;}
;   const float off=base+inc-s7; const float NL=-1.4426950408889634f;
;   *(f32x4v*)(bias+tid*8)=(f32x4v){(off+s0)*NL,(off+s1)*NL,(off+s2)*NL,(off+s3)*NL};
;   *(f32x4v*)(bias+tid*8+4)=(f32x4v){(off+s4)*NL,(off+s5)*NL,(off+s6)*NL,(off+s7)*NL};
;   if(gdst){ *(f32x4v*)(gdst+tid*8)=(f32x4v){(off+s0)*NL,(off+s1)*NL,(off+s2)*NL,(off+s3)*NL}; *(f32x4v*)(gdst+tid*8+4)=(f32x4v){(off+s4)*NL,(off+s5)*NL,(off+s6)*NL,(off+s7)*NL}; }
;   asm volatile("s_waitcnt lgkmcnt(0)\n\ts_barrier":::"memory");
; }
; __device__ __forceinline__ void j0_table(const char*shm,float gap,int*dst,int wave,int lane){
;   const __attribute__((address_space(3))) float*bl=(const __attribute__((address_space(3))) float*)((const __attribute__((address_space(3))) char*)shm+LDS_BIAS);
;   const float v=bl[64*lane+63];
;   #pragma unroll
;   for(int q=0;q<2;++q){ const int qb=2*wave+q; const float thr=bl[QB*qb]-gap; const unsigned long long mk=__ballot(v>=thr);
;     int j0=mk?(int)__builtin_ctzll(mk):0; j0&=~1; const int jmax=4*qb; j0=j0<jmax?j0:jmax; if(lane==0)dst[qb]=j0; }
; __device__ __forceinline__ float qk_bound(const float* q_g, const float* k_g, int lane) {
;     float gq = fabsf(q_g[lane]), gk = fabsf(k_g[lane]);
; #pragma unroll
;     for (int o = 1; o < 64; o <<= 1) { gq = fmaxf(gq, __shfl_xor(gq, o)); gk = fmaxf(gk, __shfl_xor(gk, o)); }
;     return attn_body::C2 * 64.0f * 1.02f * gq * gk;
.LBB0_199:
	s_or_b64 exec, exec, s[4:5]
	s_mov_b64 s[4:5], s[0:1]
	s_waitcnt lgkmcnt(0)
	s_barrier
	v_mov_b32_e32 v12, v0
	s_mov_b32 s14, s2
	s_load_dwordx4 s[8:11], s[4:5], 0x38
	s_load_dwordx2 s[12:13], s[4:5], 0x70
	s_load_dword s3, s[24:25], 0x0
	v_lshlrev_b32_e32 v170, 3, v0
	v_mov_b32_e32 v7, 0
	v_readfirstlane_b32 s16, v12
	s_cmp_gt_i32 s14, 63
	s_waitcnt lgkmcnt(0)
	s_mov_b32 s29, s3
	v_and_b32_e32 v1, 63, v0
	s_cbranch_scc1 .LBB0_223
	s_ashr_i32 s15, s14, 31
	s_lshl_b64 s[4:5], s[14:15], 14
	s_add_u32 s4, s12, s4
	s_addc_u32 s5, s13, s5
	v_lshlrev_b32_e32 v6, 2, v170
	v_lshl_add_u64 v[8:9], s[4:5], 0, v[6:7]
	s_mov_b32 s4, 0x100000
	v_add_co_u32_e32 v2, vcc, s4, v8
	s_mov_b64 s[4:5], 0x100000
	s_nop 0
	v_addc_co_u32_e32 v3, vcc, 0, v9, vcc
	global_load_dwordx4 v[2:5], v[2:3], off
	v_lshl_add_u64 v[8:9], v[8:9], 0, s[4:5]
	global_load_dwordx4 v[14:17], v[8:9], off offset:16
	s_waitcnt vmcnt(1)
	v_add_f32_e32 v3, v2, v3
	v_add_f32_e32 v10, v4, v3
	v_add_f32_e32 v11, v5, v10
	s_waitcnt vmcnt(0)
	v_add_f32_e32 v8, v14, v11
	v_add_f32_e32 v9, v15, v8
	v_add_f32_e32 v4, v16, v9
	v_add_f32_e32 v5, v17, v4
	v_mov_b32_e32 v7, v5
	s_nop 1
	v_add_f32_dpp v7, v7, v7 row_shr:1 row_mask:0xf bank_mask:0xf
	s_nop 1
	v_add_f32_dpp v7, v7, v7 row_shr:2 row_mask:0xf bank_mask:0xf
	s_nop 1
	v_add_f32_dpp v7, v7, v7 row_shr:4 row_mask:0xf bank_mask:0xf
	s_nop 1
	v_add_f32_dpp v7, v7, v7 row_shr:8 row_mask:0xf bank_mask:0xf
	s_nop 1
	v_add_f32_dpp v7, v7, v7 row_bcast:15 row_mask:0xa bank_mask:0xf
	s_nop 1
	v_add_f32_dpp v7, v7, v7 row_bcast:31 row_mask:0xc bank_mask:0xf
	v_cmp_eq_u32_e32 vcc, 63, v1
	v_mov_b32_e32 v13, v7
	s_and_saveexec_b64 s[4:5], vcc
	v_lshrrev_b32_e32 v14, 4, v0
	v_and_b32_e32 v14, 28, v14
	v_add_u32_e32 v14, 0, v14
	ds_write_b32 v14, v13 offset:49152
	s_or_b64 exec, exec, s[4:5]
	s_waitcnt lgkmcnt(0)
	s_barrier
	v_mov_b32_e32 v15, 0
	ds_read_b128 v[20:23], v15 offset:49152
	ds_read_b128 v[24:27], v15 offset:49168
	v_mov_b32_e32 v14, 0
	s_lshl_b64 s[4:5], s[14:15], 12
	s_waitcnt lgkmcnt(0)
	v_cmp_lt_u32_e32 vcc, 63, v0
	v_cndmask_b32_e32 v15, 0, v20, vcc
	v_add_f32_e32 v14, v14, v15
	v_cmp_lt_u32_e32 vcc, 0x7f, v0
	v_cndmask_b32_e32 v15, 0, v21, vcc
	v_add_f32_e32 v14, v14, v15
	v_cmp_lt_u32_e32 vcc, 0xbf, v0
	v_cndmask_b32_e32 v15, 0, v22, vcc
	v_add_f32_e32 v14, v14, v15
	v_cmp_lt_u32_e32 vcc, 0xff, v0
	v_cndmask_b32_e32 v15, 0, v23, vcc
	v_add_f32_e32 v14, v14, v15
	v_cmp_lt_u32_e32 vcc, 0x13f, v0
	v_cndmask_b32_e32 v15, 0, v24, vcc
	v_add_f32_e32 v14, v14, v15
	v_cmp_lt_u32_e32 vcc, 0x17f, v0
	v_cndmask_b32_e32 v15, 0, v25, vcc
	v_add_f32_e32 v14, v14, v15
	v_cmp_lt_u32_e32 vcc, 0x1bf, v0
	v_cndmask_b32_e32 v15, 0, v26, vcc
	v_add_f32_e32 v14, v14, v15
	v_cmp_lt_u32_e32 vcc, 0x1ff, v0
	v_cndmask_b32_e32 v15, 0, v27, vcc
	v_add_f32_e32 v14, v14, v15
	s_lshl_b64 s[4:5], s[4:5], 2
	v_cmp_gt_u32_e32 vcc, 32, v1
	s_add_u32 s4, s12, s4
	s_addc_u32 s5, s13, s5
	v_cndmask_b32_e32 v7, v13, v7, vcc
	s_add_i32 s17, 0, 0x14800
	v_add_f32_e32 v7, v7, v14
	v_lshl_add_u32 v15, v170, 2, s17
	v_sub_f32_e32 v14, v7, v5
	v_pk_add_f32 v[2:3], v[2:3], v[14:15] op_sel_hi:[1,0]
	v_pk_add_f32 v[10:11], v[10:11], v[14:15] op_sel_hi:[1,0]
	s_mov_b32 s6, 0xbfb8aa3b
	v_and_b32_e32 v16, 63, v12
	v_pk_mul_f32 v[12:13], v[10:11], s[6:7] op_sel_hi:[1,0]
	v_pk_mul_f32 v[10:11], v[2:3], s[6:7] op_sel_hi:[1,0]
	v_pk_add_f32 v[2:3], v[8:9], v[14:15] op_sel_hi:[1,0]
	v_pk_add_f32 v[4:5], v[4:5], v[14:15] op_sel_hi:[1,0]
	v_mov_b32_e32 v7, 0
	v_pk_mul_f32 v[4:5], v[4:5], s[6:7] op_sel_hi:[1,0]
	v_pk_mul_f32 v[2:3], v[2:3], s[6:7] op_sel_hi:[1,0]
	v_lshl_add_u64 v[8:9], s[4:5], 0, v[6:7]
	s_mov_b64 s[4:5], 0x1c000000
	ds_write_b128 v15, v[10:13]
	ds_write_b128 v15, v[2:5] offset:16
	v_lshl_add_u64 v[14:15], v[8:9], 0, s[4:5]
	s_brev_b32 s4, 56
	v_add_co_u32_e32 v8, vcc, s4, v8
	s_lshl_b32 s4, s14, 4
	s_nop 0
	v_addc_co_u32_e32 v9, vcc, 0, v9, vcc
	global_store_dwordx4 v[8:9], v[10:13], off
	global_store_dwordx4 v[14:15], v[2:5], off offset:16
	s_waitcnt lgkmcnt(0)
	s_barrier
	s_ashr_i32 s5, s4, 31
	s_ashr_i32 s7, s16, 6
	v_lshlrev_b32_e32 v2, 2, v16
	global_load_dword v3, v2, s[8:9]
	global_load_dword v4, v2, s[10:11]
	s_lshl_b64 s[4:5], s[4:5], 2
	s_add_u32 s4, s12, s4
	s_addc_u32 s5, s13, s5
	s_add_u32 s15, s4, 0x1c100000
	s_addc_u32 s20, s5, 0
	s_lshl_b32 s4, s7, 11
	v_lshl_add_u32 v6, v16, 8, s17
	s_add_i32 s4, s17, s4
	v_mov_b32_e32 v9, s4
	s_lshl_b32 s6, s7, 1
	v_cmp_eq_u32_e32 vcc, 0, v16
	ds_read_b32 v2, v6 offset:252
	ds_read_b32 v6, v9
	s_waitcnt vmcnt(0)
	v_max_f32_e64 v3, |v3|, |v3|
	v_max_f32_e64 v4, |v4|, |v4|
	s_nop 1
	v_max_f32_dpp v20, v3, v3 quad_perm:[1,0,3,2] row_mask:0xf bank_mask:0xf
	v_max_f32_dpp v21, v4, v4 quad_perm:[1,0,3,2] row_mask:0xf bank_mask:0xf
	s_nop 0
	v_max_f32_dpp v3, v20, v20 quad_perm:[2,3,0,1] row_mask:0xf bank_mask:0xf
	v_max_f32_dpp v4, v21, v21 quad_perm:[2,3,0,1] row_mask:0xf bank_mask:0xf
	s_nop 0
	v_max_f32_dpp v20, v3, v3 row_half_mirror row_mask:0xf bank_mask:0xf
	v_max_f32_dpp v21, v4, v4 row_half_mirror row_mask:0xf bank_mask:0xf
	s_nop 0
	v_max_f32_dpp v3, v20, v20 row_mirror row_mask:0xf bank_mask:0xf
	v_max_f32_dpp v4, v21, v21 row_mirror row_mask:0xf bank_mask:0xf
	v_mov_b32_e32 v20, v3
	v_mov_b32_e32 v21, v4
	s_nop 1
	v_permlane16_swap_b32_e32 v20, v3
	v_permlane16_swap_b32_e32 v21, v4
	v_max_f32_e32 v3, v20, v3
	v_max_f32_e32 v4, v21, v4
	v_mov_b32_e32 v20, v3
	v_mov_b32_e32 v21, v4
	s_nop 1
	v_permlane32_swap_b32_e32 v20, v3
	v_permlane32_swap_b32_e32 v21, v4
	v_max_f32_e32 v20, v20, v3
	v_max_f32_e32 v3, v21, v4
	v_mov_b32_e32 v4, v20
	v_mul_f32_e32 v4, 0x413c5bb7, v4
	v_mul_f32_e32 v3, v4, v3
	v_fmaak_f32 v3, 2.0, v3, 0x42180000
	s_waitcnt lgkmcnt(0)
	v_sub_f32_e32 v4, v6, v3
	v_cmp_ge_f32_e64 s[4:5], v2, v4
	s_and_saveexec_b64 s[16:17], vcc
	s_cbranch_execz .LBB0_220
	s_ff1_i32_b64 s21, s[4:5]
	s_and_b32 s21, s21, 62
	s_cmp_lg_u64 s[4:5], 0
	s_cselect_b32 s4, s21, 0
	s_lshl_b32 s5, s7, 3
	s_ashr_i32 s7, s6, 31
	s_min_i32 s21, s4, s5
	s_lshl_b64 s[4:5], s[6:7], 2
	s_add_u32 s4, s15, s4
	s_addc_u32 s5, s20, s5
	v_mov_b32_e32 v4, s21
	global_store_dword v7, v4, s[4:5]
